# grid barrier: last XCD leader releases all XCD generation words directly (one hop less), early L1 invalidate kept
# speedup vs baseline: 1.0236x; 1.0111x over previous
.LBB0_588:
	s_or_b64 exec, exec, s[4:5]
	buffer_inv sc1
	s_waitcnt vmcnt(0)
	v_readfirstlane_b32 s2, v3
	v_sub_u32_e32 v4, 0, v2
	s_mov_b64 s[4:5], -1
	v_add_u32_e32 v3, s2, v0
	v_cvt_f32_u32_e32 v0, v2
	v_readlane_b32 s2, v215, 26
	v_readlane_b32 s3, v215, 27
	v_rcp_iflag_f32_e32 v0, v0
	s_nop 0
	v_mul_f32_e32 v0, 0x4f7ffffe, v0
	v_cvt_u32_f32_e32 v0, v0
	v_mul_lo_u32 v4, v4, v0
	v_mul_hi_u32 v4, v0, v4
	v_add_u32_e32 v0, v0, v4
	v_mul_hi_u32 v0, v3, v0
	v_mul_lo_u32 v4, v0, v2
	v_sub_u32_e32 v4, v3, v4
	v_cmp_ge_u32_e32 vcc, v4, v2
	v_add_u32_e32 v5, 1, v0
	v_add_u32_e32 v3, 1, v3
	v_cndmask_b32_e32 v0, v0, v5, vcc
	v_sub_u32_e32 v5, v4, v2
	v_cndmask_b32_e32 v4, v4, v5, vcc
	v_cmp_ge_u32_e32 vcc, v4, v2
	v_add_u32_e32 v4, 1, v0
	s_nop 0
	v_cndmask_b32_e32 v0, v0, v4, vcc
	v_mul_lo_u32 v4, v2, v0
	v_add_u32_e32 v2, v4, v2
	v_cmp_ne_u32_e32 vcc, v3, v2
	v_mov_b64_e32 v[2:3], s[2:3]
	s_mov_b32 s16, 0
	s_and_saveexec_b64 s[2:3], vcc
	s_cbranch_execz .LBB0_600
	s_mov_b32 s16, 1
	v_readlane_b32 s4, v215, 26
	v_readlane_b32 s5, v215, 27
	s_mov_b64 s[6:7], 0
	s_nop 3
	global_load_dword v2, v1, s[4:5] sc1
	s_waitcnt vmcnt(0)
	v_cmp_eq_u32_e32 vcc, v2, v0
	s_and_saveexec_b64 s[4:5], vcc
	s_cbranch_execz .LBB0_599
	s_mov_b32 s16, 1
	s_branch .LBB0_592

.LBB0_600:
	s_or_b64 exec, exec, s[2:3]
	s_and_saveexec_b64 s[2:3], s[4:5]
	s_cbranch_execz .LBB0_602
	global_atomic_add v[2:3], v146, off
	s_cmp_lg_u32 s16, 0
	s_cbranch_scc1 .Lbar_notlast
	v_readlane_b32 s10, v215, 26
	v_readlane_b32 s11, v215, 27
	s_nop 1
	s_sub_u32 s10, s10, 0x1100
	s_subb_u32 s11, s11, 0
	s_nop 4
	global_atomic_add v1, v146, s[10:11]
	global_atomic_add v1, v146, s[10:11] offset:256
	global_atomic_add v1, v146, s[10:11] offset:512
	global_atomic_add v1, v146, s[10:11] offset:768
	global_atomic_add v1, v146, s[10:11] offset:1024
	global_atomic_add v1, v146, s[10:11] offset:1280
	global_atomic_add v1, v146, s[10:11] offset:1536
	global_atomic_add v1, v146, s[10:11] offset:1792
	global_atomic_add v1, v146, s[10:11] offset:2048
	global_atomic_add v1, v146, s[10:11] offset:2304
	global_atomic_add v1, v146, s[10:11] offset:2560
	global_atomic_add v1, v146, s[10:11] offset:2816
	global_atomic_add v1, v146, s[10:11] offset:3072
	global_atomic_add v1, v146, s[10:11] offset:3328
	global_atomic_add v1, v146, s[10:11] offset:3584
	global_atomic_add v1, v146, s[10:11] offset:3840
.Lbar_notlast:
.LBB0_602:
	s_or_b64 exec, exec, s[2:3]
	s_mov_b64 s[2:3], exec
	v_mbcnt_lo_u32_b32 v0, s2, 0
	v_mbcnt_hi_u32_b32 v0, s3, v0
	v_cmp_eq_u32_e32 vcc, 0, v0
	s_waitcnt vmcnt(0)
	s_and_saveexec_b64 s[4:5], vcc
	s_cbranch_execz .LBB0_604
	s_bcnt1_i32_b64 s2, s[2:3]
	v_mov_b32_e32 v0, s2
	v_readlane_b32 s2, v215, 22
	v_readlane_b32 s3, v215, 23
	s_nop 4
